# v41 + P0 HB (bf16 x) stores write-through so the P0->P1 seam's L2 write-back finds little dirty data
# speedup vs baseline: 1.0041x; 1.0041x over previous
; __device__ __forceinline__ unsigned pk2(float lo, float hi) { return f2bf(lo) | (f2bf(hi) << 16); }
; __global__ void __launch_bounds__(NTHR, 2) mk_fwd(Args args) {
;     ...
;         for (int m = gw; m < M; m += 2 * NGW) { const int m2 = m + NGW; const bool has2 = m2 < M;
;             const f32x4* xa = (const f32x4*)(x + (size_t)m * D) + lane; const f32x4* xb = (const f32x4*)(x + (size_t)(has2 ? m2 : m) * D) + lane;
;             f32x4 va[4], vb[4];
; #pragma unroll
;             for (int j = 0; j < 4; ++j) { va[j] = xa[64 * j]; vb[j] = xb[64 * j]; }
;             float sa = 0.f, sb = 0.f;
;             char* oa = (char*)HB + ((size_t)(((m >> 8) * 16 + (lane >> 4)) * 2 + ((m >> 7) & 1)) * 16384) + pg8::lds_byte(m & 127, 4 * (lane & 15));
;             char* ob = (char*)HB + ((size_t)(((m2 >> 8) * 16 + (lane >> 4)) * 2 + ((m2 >> 7) & 1)) * 16384) + pg8::lds_byte(m2 & 127, 4 * (lane & 15));
; #pragma unroll
;             for (int j = 0; j < 4; ++j) { sa += (va[j].x * va[j].x + va[j].y * va[j].y) + (va[j].z * va[j].z + va[j].w * va[j].w); sb += (vb[j].x * vb[j].x + vb[j].y * vb[j].y) + (vb[j].z * vb[j].z + vb[j].w * vb[j].w);
;                 *(unsigned long long*)(oa + (size_t)j * (4 * 2 * 16384)) = (unsigned long long)pk2(va[j].x, va[j].y) | ((unsigned long long)pk2(va[j].z, va[j].w) << 32);
;                 if (has2) *(unsigned long long*)(ob + (size_t)j * (4 * 2 * 16384)) = (unsigned long long)pk2(vb[j].x, vb[j].y) | ((unsigned long long)pk2(vb[j].z, vb[j].w) << 32); }
;             sa = wave_sum(sa); sb = wave_sum(sb); if (lane == 0) { ssq1[m] = sa; if (has2) ssq1[m2] = sb; } }
.LBB0_57:
	s_add_i32 s8, s28, s0
	s_cmp_lt_i32 s8, 0x8000
	s_cselect_b64 s[52:53], -1, 0
	s_and_b64 s[4:5], s[52:53], exec
	s_cselect_b32 s4, s8, s0
	s_ashr_i32 s5, s4, 31
	s_lshl_b64 s[4:5], s[4:5], 12
	global_load_dwordx4 v[24:27], v[36:37], off offset:-2048
	s_waitcnt lgkmcnt(0)
	v_lshl_add_u64 v[0:1], v[34:35], 0, s[4:5]
	global_load_dwordx4 v[20:23], v[36:37], off offset:-1024
	global_load_dwordx4 v[28:31], v[0:1], off
	global_load_dwordx4 v[16:19], v[0:1], off offset:1024
	global_load_dwordx4 v[12:15], v[36:37], off
	global_load_dwordx4 v[4:7], v[36:37], off offset:1024
	global_load_dwordx4 v[8:11], v[0:1], off offset:2048
	s_nop 0
	global_load_dwordx4 v[0:3], v[0:1], off offset:3072
	s_ashr_i32 s4, s0, 4
	s_lshr_b32 s9, s0, 3
	s_ashr_i32 s33, s8, 4
	s_lshr_b32 s55, s8, 3
	s_and_b32 s4, s4, 0x7ffffff0
	s_bfe_u32 s5, s0, 0x10007
	s_and_b32 s29, s15, 0x3c0
	s_lshr_b32 s31, s15, 4
	s_and_b32 s33, s33, 0x7ffffff0
	v_and_or_b32 v32, s9, 14, v43
	v_and_or_b32 v38, s55, 14, v43
	v_or_b32_e32 v40, s4, v42
	s_bfe_u32 s54, s8, 0x10007
	s_and_b32 s31, s31, 32
	v_or_b32_e32 v39, s29, v44
	v_lshlrev_b32_e32 v32, 10, v32
	v_or_b32_e32 v41, s33, v42
	v_lshlrev_b32_e32 v54, 10, v38
	v_lshl_or_b32 v38, v40, 1, s5
	s_add_i32 s56, s18, s15
	v_bitop3_b32 v32, v39, v32, s31 bitop3:0xde
	v_lshl_or_b32 v40, v41, 1, s54
	v_ashrrev_i32_e32 v39, 31, v38
	s_and_b32 s57, s56, 0x3c0
	s_lshr_b32 s56, s56, 4
	v_ashrrev_i32_e32 v41, 31, v40
	v_lshlrev_b64 v[38:39], 14, v[38:39]
	s_and_b32 s9, s56, 32
	v_or_b32_e32 v51, s57, v44
	v_lshlrev_b64 v[40:41], 14, v[40:41]
	v_lshl_add_u64 v[38:39], s[12:13], 0, v[38:39]
	v_lshl_add_u64 v[52:53], s[12:13], 0, v[40:41]
	v_lshl_add_u64 v[40:41], v[38:39], 0, v[32:33]
	v_bitop3_b32 v32, v51, v54, s9 bitop3:0xde
	v_lshl_add_u64 v[38:39], v[52:53], 0, v[32:33]
	s_cmpk_gt_i32 s8, 0x7fff
	s_waitcnt vmcnt(7)
	v_bfe_u32 v32, v24, 16, 1
	v_bfe_u32 v51, v25, 16, 1
	v_add3_u32 v32, v24, v32, s1
	v_bfe_u32 v52, v26, 16, 1
	v_add3_u32 v51, v25, v51, s1
	v_lshrrev_b32_e32 v32, 16, v32
	v_add3_u32 v53, v26, v52, s1
	v_and_or_b32 v52, v51, s19, v32
	v_bfe_u32 v51, v27, 16, 1
	v_lshrrev_b32_e32 v32, 16, v53
	v_add3_u32 v51, v27, v51, s1
	v_and_or_b32 v53, v51, s19, v32
	global_store_dwordx2 v[40:41], v[52:53], off sc1
	s_cbranch_scc1 .LBB0_59
	s_waitcnt vmcnt(6)
	v_bfe_u32 v32, v28, 16, 1
	v_add3_u32 v32, v28, v32, s1
	v_bfe_u32 v51, v29, 16, 1
	v_lshrrev_b32_e32 v32, 16, v32
	v_add3_u32 v51, v29, v51, s1
	v_and_or_b32 v52, v51, s19, v32
	v_bfe_u32 v32, v30, 16, 1
	v_add3_u32 v32, v30, v32, s1
	v_bfe_u32 v51, v31, 16, 1
	v_lshrrev_b32_e32 v32, 16, v32
	v_add3_u32 v51, v31, v51, s1
	v_and_or_b32 v53, v51, s19, v32
	global_store_dwordx2 v[38:39], v[52:53], off sc1
.LBB0_59:
	s_waitcnt vmcnt(7)
	v_bfe_u32 v32, v20, 16, 1
	v_add3_u32 v32, v20, v32, s1
	v_bfe_u32 v51, v21, 16, 1
	v_lshrrev_b32_e32 v32, 16, v32
	v_add3_u32 v51, v21, v51, s1
	v_and_or_b32 v52, v51, s19, v32
	v_bfe_u32 v32, v22, 16, 1
	v_add3_u32 v32, v22, v32, s1
	v_bfe_u32 v51, v23, 16, 1
	v_lshrrev_b32_e32 v32, 16, v32
	v_add3_u32 v51, v23, v51, s1
	v_add_co_u32_e32 v54, vcc, 0x20000, v40
	v_and_or_b32 v53, v51, s19, v32
	s_nop 0
	v_addc_co_u32_e32 v55, vcc, 0, v41, vcc
	v_cndmask_b32_e64 v32, 0, 1, s[52:53]
	v_cmp_ne_u32_e64 s[4:5], 1, v32
	s_andn2_b64 vcc, exec, s[52:53]
	global_store_dwordx2 v[54:55], v[52:53], off sc1
	s_cbranch_vccnz .LBB0_61
	s_waitcnt vmcnt(6)
	v_bfe_u32 v32, v16, 16, 1
	v_add3_u32 v32, v16, v32, s1
	v_bfe_u32 v51, v17, 16, 1
	v_lshrrev_b32_e32 v32, 16, v32
	v_add3_u32 v51, v17, v51, s1
	v_and_or_b32 v52, v51, s19, v32
	v_bfe_u32 v32, v18, 16, 1
	v_add3_u32 v32, v18, v32, s1
	v_bfe_u32 v51, v19, 16, 1
	v_lshrrev_b32_e32 v32, 16, v32
	v_add3_u32 v51, v19, v51, s1
	v_add_co_u32_e32 v54, vcc, 0x20000, v38
	v_and_or_b32 v53, v51, s19, v32
	s_nop 0
	v_addc_co_u32_e32 v55, vcc, 0, v39, vcc
	global_store_dwordx2 v[54:55], v[52:53], off sc1
.LBB0_61:
	s_waitcnt vmcnt(5)
	v_bfe_u32 v32, v12, 16, 1
	v_add3_u32 v32, v12, v32, s1
	v_bfe_u32 v51, v13, 16, 1
	v_lshrrev_b32_e32 v32, 16, v32
	v_add3_u32 v51, v13, v51, s1
	v_and_or_b32 v52, v51, s19, v32
	v_bfe_u32 v32, v14, 16, 1
	v_add3_u32 v32, v14, v32, s1
	v_bfe_u32 v51, v15, 16, 1
	v_add_co_u32_e32 v54, vcc, 0x40000, v40
	v_lshrrev_b32_e32 v32, 16, v32
	v_add3_u32 v51, v15, v51, s1
	v_addc_co_u32_e32 v55, vcc, 0, v41, vcc
	v_and_or_b32 v53, v51, s19, v32
	s_and_b64 vcc, exec, s[4:5]
	global_store_dwordx2 v[54:55], v[52:53], off sc1
	s_cbranch_vccnz .LBB0_63
	s_waitcnt vmcnt(4)
	v_bfe_u32 v32, v8, 16, 1
	v_add3_u32 v32, v8, v32, s1
	v_bfe_u32 v51, v9, 16, 1
	v_lshrrev_b32_e32 v32, 16, v32
	v_add3_u32 v51, v9, v51, s1
	v_and_or_b32 v52, v51, s19, v32
	v_bfe_u32 v32, v10, 16, 1
	v_add3_u32 v32, v10, v32, s1
	v_bfe_u32 v51, v11, 16, 1
	v_lshrrev_b32_e32 v32, 16, v32
	v_add3_u32 v51, v11, v51, s1
	v_add_co_u32_e32 v54, vcc, 0x40000, v38
	v_and_or_b32 v53, v51, s19, v32
	s_nop 0
	v_addc_co_u32_e32 v55, vcc, 0, v39, vcc
	global_store_dwordx2 v[54:55], v[52:53], off sc1
.LBB0_63:
	s_waitcnt vmcnt(5)
	v_bfe_u32 v32, v4, 16, 1
	v_add3_u32 v32, v4, v32, s1
	v_bfe_u32 v51, v5, 16, 1
	v_lshrrev_b32_e32 v32, 16, v32
	v_add3_u32 v51, v5, v51, s1
	v_and_or_b32 v52, v51, s19, v32
	v_bfe_u32 v32, v6, 16, 1
	v_add3_u32 v32, v6, v32, s1
	v_bfe_u32 v51, v7, 16, 1
	v_add_co_u32_e32 v40, vcc, 0x60000, v40
	v_lshrrev_b32_e32 v32, 16, v32
	v_add3_u32 v51, v7, v51, s1
	v_addc_co_u32_e32 v41, vcc, 0, v41, vcc
	v_and_or_b32 v53, v51, s19, v32
	s_and_b64 vcc, exec, s[4:5]
	global_store_dwordx2 v[40:41], v[52:53], off sc1
	s_cbranch_vccnz .LBB0_65
	s_waitcnt vmcnt(4)
	v_bfe_u32 v32, v0, 16, 1
	v_add3_u32 v32, v0, v32, s1
	v_bfe_u32 v40, v1, 16, 1
	v_lshrrev_b32_e32 v32, 16, v32
	v_add3_u32 v40, v1, v40, s1
	v_and_or_b32 v40, v40, s19, v32
	v_bfe_u32 v32, v2, 16, 1
	v_add3_u32 v32, v2, v32, s1
	v_bfe_u32 v41, v3, 16, 1
	v_lshrrev_b32_e32 v32, 16, v32
	v_add3_u32 v41, v3, v41, s1
	v_add_co_u32_e32 v38, vcc, 0x60000, v38
	v_and_or_b32 v41, v41, s19, v32
	s_nop 0
	v_addc_co_u32_e32 v39, vcc, 0, v39, vcc
	global_store_dwordx2 v[38:39], v[40:41], off sc1
